# mixer-B loop: next iteration's barrier and LDS-DMA issue folded into the MFMA-only P.V tail
# speedup vs baseline: 1.1309x; 1.0083x over previous
; #define MFMA(a, b, c) __builtin_amdgcn_mfma_f32_32x32x16_bf16((a), (b), (c), 0, 0, 0)
; DI int crow(int e, int h) { return (e & 3) + 8 * (e >> 2) + 4 * h; }
; template <int NS>
; DI void attn_item(const Params& p, int layer, char* smem, VBC& vc, int b, int hq, int qblk) {
;     ...
;         auto qk = [&](const int m, f32x16 (&s)[2]) {
; #pragma unroll
;             for (int kt2 = 0; kt2 < 2; ++kt2)
; #pragma unroll
;                 for (int e = 0; e < 16; ++e) s[kt2][e] = 0.f;
;             __builtin_amdgcn_s_setprio(1);
; #pragma unroll
;             for (int ks = 0; ks < NKS; ++ks)
; #pragma unroll
;                 for (int kt2 = 0; kt2 < 2; ++kt2) s[kt2] = MFMA(ld8(cK + (kt2 * 32 + r) * 64 + (((m * DQK + ks * 16)) ^ hs16)), qf[m][ks], s[kt2]);
; #pragma unroll
;             for (int kt2 = 0; kt2 < 2; ++kt2) { uint4 qa4 = {qaug[m], 0u, 0u, 0u}; s[kt2] = MFMA(kones, __builtin_bit_cast(bf16x8, qa4), s[kt2]); }
;             __builtin_amdgcn_s_setprio(0);
;         };
;         auto softmax = [&](const int m, f32x16 (&s)[2], bf16x8 (&pf)[2][2]) {
;             const bool fixed = fast && it > 0;
;             if (NS == 1 && is_lat) {
; #pragma unroll
;                 for (int kt2 = 0; kt2 < 2; ++kt2)
; #pragma unroll
;                     for (int e = 0; e < 16; ++e) {
;                         int d = kpos0 + kt2 * 32 + crow(e, h) - qpos;
;                         if (d > 128 || d < -128) s[kt2][e] = -1e30f;
;                     }
;             }
;             if (fixed) {
;                 float ls = 0.f;
; #pragma unroll
;                 for (int kt2 = 0; kt2 < 2; ++kt2)
; #pragma unroll
;                     for (int e = 0; e < 16; ++e) { const float pv = __builtin_amdgcn_exp2f(s[kt2][e]); s[kt2][e] = pv; ls += pv; }
;                 lrun[m] += ls;
.Lr_body:
	v_lshl_add_u32 v226, s17, 1, v248
	v_lshl_add_u32 v5, v201, 1, v226
	v_lshl_add_u32 v6, v245, 1, v226
	ds_read_b128 v[112:115], v5
	ds_read_b128 v[116:119], v5 offset:4096
	v_lshl_add_u32 v223, v246, 1, v226
	ds_read_b128 v[120:123], v6
	ds_read_b128 v[124:127], v6 offset:4096
	v_lshl_add_u32 v225, v247, 1, v226
	ds_read_b128 v[128:131], v223
	ds_read_b128 v[132:135], v223 offset:4096
	ds_read_b128 v[136:139], v225
	ds_read_b128 v[140:143], v225 offset:4096
	v_mov_b32_e32 v2, 0
	v_mov_b32_e32 v3, 0
	v_mov_b32_e32 v12, s52
	v_mov_b32_e32 v13, 0
	v_mov_b32_e32 v14, 0
	v_mov_b32_e32 v15, 0
	v_mov_b32_e32 v8, v192
	v_mov_b32_e32 v9, 0
	v_mov_b32_e32 v10, 0
	v_mov_b32_e32 v11, 0
	s_waitcnt lgkmcnt(7)
	v_mfma_f32_32x32x16_bf16 v[96:111], v[112:115], v[176:179], 0
	s_waitcnt lgkmcnt(6)
	v_mfma_f32_32x32x16_bf16 v[80:95], v[116:119], v[176:179], 0
	s_waitcnt lgkmcnt(5)
	v_mfma_f32_32x32x16_bf16 v[96:111], v[120:123], v[180:183], v[96:111]
	s_waitcnt lgkmcnt(4)
	v_mfma_f32_32x32x16_bf16 v[80:95], v[124:127], v[180:183], v[80:95]
	ds_read_b128 v[112:115], v5 offset:8192
	ds_read_b128 v[116:119], v5 offset:12288
	v_mfma_f32_32x32x16_bf16 v[96:111], v[12:15], v[0:3], v[96:111]
	ds_read_b128 v[120:123], v6 offset:8192
	ds_read_b128 v[124:127], v6 offset:12288
	v_mfma_f32_32x32x16_bf16 v[80:95], v[12:15], v[0:3], v[80:95]
	s_waitcnt lgkmcnt(7)
	v_mfma_f32_32x32x16_bf16 v[144:159], v[128:131], v[184:187], 0
	s_waitcnt lgkmcnt(6)
	v_mfma_f32_32x32x16_bf16 v[160:175], v[132:135], v[184:187], 0
	s_waitcnt lgkmcnt(5)
	v_mfma_f32_32x32x16_bf16 v[144:159], v[136:139], v[188:191], v[144:159]
	s_waitcnt lgkmcnt(4)
	v_mfma_f32_32x32x16_bf16 v[160:175], v[140:143], v[188:191], v[160:175]
	ds_read_b128 v[128:131], v223 offset:8192
	ds_read_b128 v[132:135], v223 offset:12288
	v_exp_f32_e32 v96, v96
	v_exp_f32_e32 v97, v97
	v_exp_f32_e32 v98, v98
	v_exp_f32_e32 v99, v99
	v_mfma_f32_32x32x16_bf16 v[144:159], v[12:15], v[8:11], v[144:159]
	ds_read_b128 v[136:139], v225 offset:8192
	ds_read_b128 v[140:143], v225 offset:12288
	v_exp_f32_e32 v100, v100
	v_exp_f32_e32 v101, v101
	v_pk_add_f32 v[2:3], v[96:97], v[98:99]
	v_exp_f32_e32 v102, v102
	v_exp_f32_e32 v103, v103
	v_pk_add_f32 v[2:3], v[2:3], v[100:101]
	v_mfma_f32_32x32x16_bf16 v[160:175], v[12:15], v[8:11], v[160:175]
	v_exp_f32_e32 v104, v104
	v_exp_f32_e32 v105, v105
	v_pk_add_f32 v[2:3], v[2:3], v[102:103]
	v_exp_f32_e32 v106, v106
	v_exp_f32_e32 v107, v107
	v_pk_add_f32 v[2:3], v[2:3], v[104:105]
	v_exp_f32_e32 v108, v108
	v_exp_f32_e32 v109, v109
	v_pk_add_f32 v[2:3], v[2:3], v[106:107]
	v_exp_f32_e32 v110, v110
	v_exp_f32_e32 v111, v111
	v_pk_add_f32 v[2:3], v[2:3], v[108:109]
	v_exp_f32_e32 v80, v80
	v_exp_f32_e32 v81, v81
	v_pk_add_f32 v[2:3], v[2:3], v[110:111]
	v_exp_f32_e32 v82, v82
	v_exp_f32_e32 v83, v83
	v_pk_add_f32 v[2:3], v[2:3], v[80:81]
	v_exp_f32_e32 v84, v84
	v_exp_f32_e32 v85, v85
	v_pk_add_f32 v[2:3], v[2:3], v[82:83]
	v_exp_f32_e32 v86, v86
	v_exp_f32_e32 v87, v87
	v_pk_add_f32 v[2:3], v[2:3], v[84:85]
	v_exp_f32_e32 v88, v88
	v_exp_f32_e32 v89, v89
	v_pk_add_f32 v[2:3], v[2:3], v[86:87]
	v_exp_f32_e32 v90, v90
	v_exp_f32_e32 v91, v91
	v_pk_add_f32 v[2:3], v[2:3], v[88:89]
	v_exp_f32_e32 v92, v92
	v_exp_f32_e32 v93, v93
	v_pk_add_f32 v[2:3], v[2:3], v[90:91]
	v_exp_f32_e32 v94, v94
	v_exp_f32_e32 v95, v95
	v_pk_add_f32 v[2:3], v[2:3], v[92:93]
	v_mov_b32_e32 v96, v96
	v_pk_add_f32 v[2:3], v[2:3], v[94:95]
	v_cvt_pk_bf16_f32 v96, v96, v97
	v_cvt_pk_bf16_f32 v97, v98, v99
	v_cvt_pk_bf16_f32 v98, v100, v101
	v_cvt_pk_bf16_f32 v99, v102, v103
	v_cvt_pk_bf16_f32 v100, v104, v105
	v_cvt_pk_bf16_f32 v101, v106, v107
	v_cvt_pk_bf16_f32 v102, v108, v109
	v_cvt_pk_bf16_f32 v103, v110, v111
	v_cvt_pk_bf16_f32 v80, v80, v81
	v_cvt_pk_bf16_f32 v81, v82, v83
	v_cvt_pk_bf16_f32 v82, v84, v85
	v_cvt_pk_bf16_f32 v83, v86, v87
	v_cvt_pk_bf16_f32 v84, v88, v89
	v_cvt_pk_bf16_f32 v85, v90, v91
	v_cvt_pk_bf16_f32 v86, v92, v93
	v_cvt_pk_bf16_f32 v87, v94, v95
	v_add_f32_e32 v2, v2, v3
	v_add_f32_e32 v194, v194, v2
	s_waitcnt lgkmcnt(7)
	v_mfma_f32_32x32x16_bf16 v[64:79], v[112:115], v[96:99], v[64:79]
	v_exp_f32_e32 v144, v144
	v_exp_f32_e32 v145, v145
	v_exp_f32_e32 v146, v146
	v_exp_f32_e32 v147, v147
	v_exp_f32_e32 v148, v148
	v_exp_f32_e32 v149, v149
	v_pk_add_f32 v[14:15], v[144:145], v[146:147]
	v_exp_f32_e32 v150, v150
	s_waitcnt lgkmcnt(6)
	v_mfma_f32_32x32x16_bf16 v[32:47], v[116:119], v[96:99], v[32:47]
	v_exp_f32_e32 v151, v151
	v_pk_add_f32 v[14:15], v[14:15], v[148:149]
	v_exp_f32_e32 v152, v152
	v_exp_f32_e32 v153, v153
	v_pk_add_f32 v[14:15], v[14:15], v[150:151]
	v_exp_f32_e32 v154, v154
	v_exp_f32_e32 v155, v155
	v_pk_add_f32 v[14:15], v[14:15], v[152:153]
	s_waitcnt lgkmcnt(5)
	v_mfma_f32_32x32x16_bf16 v[64:79], v[120:123], v[100:103], v[64:79]
	v_exp_f32_e32 v156, v156
	v_exp_f32_e32 v157, v157
	v_pk_add_f32 v[14:15], v[14:15], v[154:155]
	v_exp_f32_e32 v158, v158
	v_exp_f32_e32 v159, v159
	v_pk_add_f32 v[14:15], v[14:15], v[156:157]
	v_exp_f32_e32 v160, v160
	v_exp_f32_e32 v161, v161
	s_waitcnt lgkmcnt(4)
	v_mfma_f32_32x32x16_bf16 v[32:47], v[124:127], v[100:103], v[32:47]
	v_pk_add_f32 v[14:15], v[14:15], v[158:159]
	v_exp_f32_e32 v162, v162
	v_exp_f32_e32 v163, v163
	v_pk_add_f32 v[14:15], v[14:15], v[160:161]
	v_exp_f32_e32 v164, v164
	v_exp_f32_e32 v165, v165
	v_pk_add_f32 v[14:15], v[14:15], v[162:163]
	v_exp_f32_e32 v166, v166
	s_waitcnt lgkmcnt(3)
	v_mfma_f32_32x32x16_bf16 v[64:79], v[128:131], v[80:83], v[64:79]
	v_exp_f32_e32 v167, v167
	v_pk_add_f32 v[14:15], v[14:15], v[164:165]
	v_exp_f32_e32 v168, v168
	v_exp_f32_e32 v169, v169
	v_pk_add_f32 v[14:15], v[14:15], v[166:167]
	v_exp_f32_e32 v170, v170
	v_exp_f32_e32 v171, v171
	v_pk_add_f32 v[14:15], v[14:15], v[168:169]
	s_waitcnt lgkmcnt(2)
	v_mfma_f32_32x32x16_bf16 v[32:47], v[132:135], v[80:83], v[32:47]
	v_exp_f32_e32 v172, v172
	v_exp_f32_e32 v173, v173
	v_pk_add_f32 v[14:15], v[14:15], v[170:171]
	v_exp_f32_e32 v174, v174
	v_exp_f32_e32 v175, v175
	v_pk_add_f32 v[14:15], v[14:15], v[172:173]
	v_mov_b32_e32 v144, v144
	v_pk_add_f32 v[14:15], v[14:15], v[174:175]
	s_waitcnt lgkmcnt(1)
	v_mfma_f32_32x32x16_bf16 v[64:79], v[136:139], v[84:87], v[64:79]
	s_waitcnt lgkmcnt(0)
	v_mfma_f32_32x32x16_bf16 v[32:47], v[140:143], v[84:87], v[32:47]
	v_cvt_pk_bf16_f32 v144, v144, v145
	v_cvt_pk_bf16_f32 v145, v146, v147
	v_cvt_pk_bf16_f32 v146, v148, v149
	v_cvt_pk_bf16_f32 v147, v150, v151
	v_cvt_pk_bf16_f32 v148, v152, v153
	v_cvt_pk_bf16_f32 v149, v154, v155
	v_cvt_pk_bf16_f32 v150, v156, v157
	v_cvt_pk_bf16_f32 v151, v158, v159
	v_cvt_pk_bf16_f32 v160, v160, v161
	v_cvt_pk_bf16_f32 v161, v162, v163
	v_cvt_pk_bf16_f32 v162, v164, v165
	v_cvt_pk_bf16_f32 v163, v166, v167
	v_cvt_pk_bf16_f32 v164, v168, v169
	v_cvt_pk_bf16_f32 v165, v170, v171
	v_cvt_pk_bf16_f32 v166, v172, v173
	v_cvt_pk_bf16_f32 v167, v174, v175
	v_add_f32_e32 v193, v14, v15
	v_add_f32_e32 v4, v4, v193
	s_nop 1
	s_cmp_lg_u32 s46, s44
	s_cbranch_scc0 .Lr_last
; #define MFMA(a, b, c) __builtin_amdgcn_mfma_f32_32x32x16_bf16((a), (b), (c), 0, 0, 0)
; template <int NS>
; DI void attn_item(const Params& p, int layer, char* smem, VBC& vc, int b, int hq, int qblk) {
;     ...
;     auto dma_tile = [&](int it, int st) {
;         const u16 *kp, *vp; tile_ptrs(it, kp, vp);
; #pragma unroll
;         for (int i = 0; i < 2; ++i) {
;             const int row = wave4 * 16 + i * 8 + drow;
;             const int chunk = dslot ^ ((row >> 1) & 7);
;             lds_u32* dk = (lds_u32*)(sK + st * 8192 + (wave4 * 16 + i * 8) * 64);
;             lds_u32* dv = (lds_u32*)(sK + st * 8192 + 4096 + (wave4 * 16 + i * 8) * 64);
;             __builtin_amdgcn_global_load_lds((const unsigned*)(kp + (size_t)row * PC + chunk * 8), dk, 16, 0, 0);
;             __builtin_amdgcn_global_load_lds((const unsigned*)(vp + (size_t)row * KVS + chunk * 8), dv, 16, 0, 0);
;         }
;     };
;     ...
;         auto pvm = [&](const int m, const bf16x8 (&pf)[2][2]) {
;             __builtin_amdgcn_s_setprio(1);
; #pragma unroll
;             for (int kk = 0; kk < 4; ++kk)
; #pragma unroll
;                 for (int dvt = 0; dvt < 2; ++dvt) O[m][dvt] = MFMA(ld8(cV + (dvt * 32 + r) * 64 + ((kk * 16) ^ hs16)), pf[kk >> 1][kk & 1], O[m][dvt]);
;             __builtin_amdgcn_s_setprio(0);
;         };
	v_mfma_f32_32x32x16_bf16 v[48:63], v[112:115], v[144:147], v[48:63]
	s_waitcnt vmcnt(0)
	v_mov_b32_e32 v2, s16
	v_mov_b32_e32 v3, s46
	s_mov_b64 exec, 1
	ds_write_b32 v2, v3
	s_mov_b64 exec, -1
	s_add_i32 s0, s33, 0x10000
	v_mov_b32_e32 v6, s0
	ds_read_b128 v[8:11], v6
	v_mfma_f32_32x32x16_bf16 v[16:31], v[116:119], v[144:147], v[16:31]
	s_add_i32 s54, s46, -1
	s_max_i32 s54, s54, 1
	s_add_i32 s47, s46, 3
	s_and_b32 s55, s47, 3
	s_lshl_b32 s55, s55, 14
	s_cmp_lt_u32 s47, s21
	s_cselect_b64 s[0:1], -1, 0
	s_sub_i32 s17, s47, s21
	s_min_u32 s17, s47, s17
	s_and_b64 s[0:1], s[0:1], exec
	s_cselect_b32 s0, s20, s27
	s_cselect_b32 s1, s25, s41
	s_cselect_b32 s48, s24, s40
	s_lshl_b32 s49, s17, 6
	s_add_i32 s49, s49, s0
	s_lshl_b32 s0, s17, 7
	s_add_u32 s0, s48, s0
	s_addc_u32 s1, s1, 0
	s_mul_hi_i32 s17, s49, 0x1a80
	s_mulk_i32 s49, 0x1a80
	s_add_u32 s48, s42, s49
	s_addc_u32 s49, s43, s17
	v_mfma_f32_32x32x16_bf16 v[48:63], v[120:123], v[148:151], v[48:63]
	v_add_u32_e32 v2, v206, v222
	v_add_u32_e32 v3, v208, v222
	v_add_u32_e32 v5, v210, v224
	s_waitcnt lgkmcnt(0)
	v_min3_u32 v8, v8, v9, v10
	v_min_u32_e32 v8, v8, v11
	v_mfma_f32_32x32x16_bf16 v[16:31], v[124:127], v[148:151], v[16:31]
	v_cmp_gt_u32_e32 vcc, s54, v8
	s_cbranch_vccnz .Lr_pollslow
.Lr_ready:
	s_cmp_lt_u32 s47, s26
	s_cbranch_scc0 .Lr_nodma
	s_add_i32 m0, s98, s55
	v_add_u32_e32 v6, v212, v224
	global_load_lds_dwordx4 v2, s[48:49]
	v_mfma_f32_32x32x16_bf16 v[48:63], v[128:131], v[160:163], v[48:63]
	s_add_i32 m0, m0, 0x2000
	s_nop 0
	global_load_lds_dwordx4 v3, s[0:1]
	v_mfma_f32_32x32x16_bf16 v[16:31], v[132:135], v[160:163], v[16:31]
	s_add_i32 m0, s99, s55
	s_nop 0
	global_load_lds_dwordx4 v5, s[48:49]
	v_mfma_f32_32x32x16_bf16 v[48:63], v[136:139], v[164:167], v[48:63]
	s_add_i32 m0, m0, 0x2000
	s_nop 0
	global_load_lds_dwordx4 v6, s[0:1]
	v_mfma_f32_32x32x16_bf16 v[16:31], v[140:143], v[164:167], v[16:31]
	s_branch .Lr_next
.Lr_nodma:
	v_mfma_f32_32x32x16_bf16 v[48:63], v[128:131], v[160:163], v[48:63]
	v_mfma_f32_32x32x16_bf16 v[16:31], v[132:135], v[160:163], v[16:31]
	v_mfma_f32_32x32x16_bf16 v[48:63], v[136:139], v[164:167], v[48:63]
	v_mfma_f32_32x32x16_bf16 v[16:31], v[140:143], v[164:167], v[16:31]
.Lr_next:
	s_add_i32 s46, s46, 1
	s_and_b32 s17, s46, 3
	s_lshl_b32 s17, s17, 13
	s_branch .Lr_body
.Lr_pollslow:
	s_sleep 1
	v_mov_b32_e32 v6, s33
	v_add_u32_e32 v6, 0x10000, v6
	ds_read_b128 v[8:11], v6
	s_waitcnt lgkmcnt(0)
	v_min3_u32 v8, v8, v9, v10
	v_min_u32_e32 v8, v8, v11
	v_cmp_gt_u32_e32 vcc, s54, v8
	s_cbranch_vccnz .Lr_pollslow
	s_branch .Lr_ready
.Lr_last:
	v_mfma_f32_32x32x16_bf16 v[48:63], v[112:115], v[144:147], v[48:63]
	v_mfma_f32_32x32x16_bf16 v[16:31], v[116:119], v[144:147], v[16:31]
	v_mfma_f32_32x32x16_bf16 v[48:63], v[120:123], v[148:151], v[48:63]
	v_mfma_f32_32x32x16_bf16 v[16:31], v[124:127], v[148:151], v[16:31]
	v_mfma_f32_32x32x16_bf16 v[48:63], v[128:131], v[160:163], v[48:63]
	v_mfma_f32_32x32x16_bf16 v[16:31], v[132:135], v[160:163], v[16:31]
	v_mfma_f32_32x32x16_bf16 v[48:63], v[136:139], v[164:167], v[48:63]
	v_mfma_f32_32x32x16_bf16 v[16:31], v[140:143], v[164:167], v[16:31]
	v_mov_b32_e32 v223, v194
	v_mov_b32_e32 v193, v4
	v_mov_b32_e32 v226, v7
	v_mov_b32_e32 v3, v0
	v_mov_b32_e32 v0, v249
	v_mov_b32_e32 v195, v192
	s_waitcnt vmcnt(0)
	s_add_i32 s45, s45, -4
	s_branch .LBB0_964
